# GEMM phase start: no wait for the row-statistic zeroing stores' acknowledgement before the tile set-up (workgroups 0-31 started each such phase late)
# speedup vs baseline: 1.0007x; 1.0007x over previous
; #define PG8_BAR __builtin_amdgcn_s_barrier()
; template <class Epi, class Sched, bool ALIGN_EPI = false, bool SP2 = false>
; __device__ __forceinline__ void gemm_phase(PG8_LAS unsigned char* lds, const Gemm g, const Sched S, const Epi E) {
;     const int tid = tid_opq(), wid = __builtin_amdgcn_readfirstlane(tid >> 6), lane = tid & 63, wr = wid >> 2, wc = wid & 3, fr = lane & 15, fq = lane >> 4;
;     const int K = g.K, nt = K / BK;
;     unsigned voffA[2], voffB[2];
; #pragma unroll
;     for (int i = 0; i < 2; ++i) { int R, C; stage_rc(tid * 16 + i * 8192, R, C); const int Rb = Epi::PERM ? ((R & ~31) + perm32(R & 31)) : R;
;         voffA[i] = (unsigned)(R * K + C) * 2u; voffB[i] = (unsigned)(Rb * K + C) * 2u; }
;     const size_t kstep = (size_t)(BK * 2);
;     const size_t hstep = (size_t)HALF * K * 2;
;     const size_t tstep = 2 * hstep;
;     const unsigned ldsw = (unsigned)wid * 1024u;
;     const int aoff = lds_byte(wr * 64 + fr, fq * 8), boff = lds_byte(wc * 32 + fr, fq * 8);
;     ...
;     Unit cur, nxt; int ui = 0;
;     if (!S.next(0, cur)) return;
;     f32x4 acc[2][2][4][2];
;     E.init_acc(acc, cur, wr, wc, fr, fq);
;     bf16x8 At[4][2], B0[2][2], B1[2][2];
;     const char* cA = (const char*)g.A + (size_t)cur.pm * tstep; const char* cB = (const char*)g.Bt + (size_t)cur.pn * tstep;
;     S.a_ready(cur);
;     float pre[8]; E.prefetch(cur, wr, fr, pre);
;     if constexpr (SP2) {
;         PG8_STAGE(PG8_SB(0, 0), cB, voffB); PG8_STAGE(PG8_SB(0, 1), cB + hstep, voffB); PG8_STAGE(PG8_SA(0, 0), cA, voffA); PG8_STAGE(PG8_SA(0, 1), cA + hstep, voffA);
;         if (wr == 1) PG8_BAR;
;         PG8_WAIT_V(2); PG8_BAR;
;         PG8_STAGE(PG8_SB(1, 0), cB + kstep, voffB); PG8_STAGE(PG8_SA(1, 0), cA + kstep, voffA); PG8_STAGE(PG8_SB(1, 1), cB + hstep + kstep, voffB);
;         PG8_WAIT_V(6); PG8_BAR;
;     } else {
;         PG8_STAGE(PG8_SB(0, 0), cB, voffB); PG8_STAGE(PG8_SA(0, 0), cA, voffA); PG8_STAGE(PG8_SB(0, 1), cB + hstep, voffB); PG8_STAGE(PG8_SA(0, 1), cA + hstep, voffA);
;         if (wr == 1) PG8_BAR;
;         PG8_WAIT_V(4); PG8_BAR;
;     __device__ bool next(int i, Unit& u) const {
;         const long L = (long)i * G + c; if (L >= nwg) return false;
;         int wgid = (int)L; { const int q = nwg / 8, r = nwg % 8, xcd = wgid % 8, off = wgid / 8; wgid = (xcd < r ? xcd * (q + 1) : r * (q + 1) + (xcd - r) * q) + off; }
.LBB0_166:
	s_and_b64 s[14:15], s[16:17], exec
	v_readlane_b32 s14, v252, 24
	v_readlane_b32 s15, v252, 25
	s_cselect_b32 s51, s15, s97
	s_cselect_b32 s50, s14, s96
	s_andn2_b64 vcc, exec, s[0:1]
	s_cbranch_vccnz .LBB0_187
	s_mov_b32 s0, s2
	s_ashr_i32 s1, s0, 31
	s_and_b32 s60, s1, s34
	s_lshr_b32 s38, s77, 2
	s_add_i32 s60, s60, s0
	v_mov_b32_e32 v21, v187
	s_cmp_ge_i32 s60, s38
	v_readfirstlane_b32 s1, v21
	s_cbranch_scc1 .LBB0_187
	v_lshlrev_b32_e32 v0, 4, v21
	v_add_u32_e32 v2, 0x2000, v0
	s_waitcnt lgkmcnt(1)
	v_ashrrev_i32_e32 v3, 31, v2
	v_lshrrev_b32_e32 v3, 22, v3
	v_add_u32_e32 v3, v2, v3
	v_ashrrev_i32_e32 v3, 10, v3
	s_waitcnt lgkmcnt(0)
	v_mul_i32_i24_e32 v4, 0x400, v3
	v_sub_u32_e32 v2, v2, v4
	v_lshrrev_b32_e32 v4, 4, v2
	v_bitop3_b32 v2, v4, v2, 32 bitop3:0x6c
	v_ashrrev_i32_e32 v4, 31, v2
	v_lshrrev_b32_e32 v4, 26, v4
	v_add_u32_e32 v4, v2, v4
	v_lshlrev_b32_e32 v6, 3, v3
	v_ashrrev_i32_e32 v5, 6, v4
	v_and_b32_e32 v6, -16, v6
	v_lshlrev_b32_e32 v3, 5, v3
	v_add_u32_e32 v6, v5, v6
	v_and_b32_e32 v14, 32, v3
	v_and_b32_e32 v3, 0xc0, v4
	v_and_b32_e32 v5, 3, v5
	s_mov_b32 s0, 0x7fffffe0
	v_lshrrev_b32_e32 v7, 2, v6
	v_lshlrev_b32_e32 v8, 1, v6
	v_sub_u32_e32 v2, v2, v3
	v_and_or_b32 v5, v6, s0, v5
	v_and_b32_e32 v7, 4, v7
	v_and_b32_e32 v8, 24, v8
	v_ashrrev_i16_sdwa v2, v188, sext(v2) dst_sel:DWORD dst_unused:UNUSED_PAD src0_sel:DWORD src1_sel:BYTE_0
	v_or3_b32 v5, v5, v7, v8
	v_bfe_i32 v15, v2, 0, 16
	v_mul_lo_u32 v5, v5, s76
	v_add_u32_e32 v2, v14, v15
	v_mul_lo_u32 v16, v6, s76
	v_add_lshl_u32 v130, v5, v2, 1
	v_add_lshl_u32 v132, v2, v16, 1
	v_bfe_i32 v2, v21, 27, 1
	v_lshrrev_b32_e32 v2, 22, v2
	v_add_u32_e32 v2, v0, v2
	v_and_b32_e32 v2, 0xfffffc00, v2
	v_sub_u32_e32 v0, v0, v2
	v_ashrrev_i32_e32 v3, 31, v21
	v_lshrrev_b32_e32 v2, 4, v0
	v_lshrrev_b32_e32 v3, 26, v3
	v_bitop3_b32 v2, v2, v0, 32 bitop3:0x6c
	v_ashrrev_i32_e32 v0, 31, v0
	v_add_u32_e32 v3, v21, v3
	v_lshrrev_b32_e32 v0, 26, v0
	v_ashrrev_i32_e32 v3, 6, v3
	v_add_u32_e32 v0, v2, v0
	v_lshlrev_b32_e32 v4, 3, v3
	v_ashrrev_i32_e32 v0, 6, v0
	v_and_b32_e32 v4, -16, v4
	v_add_u32_e32 v4, v0, v4
	v_and_b32_e32 v5, 3, v0
	v_mul_i32_i24_e32 v0, 64, v0
	v_lshrrev_b32_e32 v6, 2, v4
	v_lshlrev_b32_e32 v7, 1, v4
	v_sub_u32_e32 v0, v2, v0
	v_and_or_b32 v5, v4, s0, v5
	v_and_b32_e32 v6, 4, v6
	v_and_b32_e32 v7, 24, v7
	v_lshlrev_b32_e32 v3, 5, v3
	v_ashrrev_i16_sdwa v0, v188, sext(v0) dst_sel:DWORD dst_unused:UNUSED_PAD src0_sel:DWORD src1_sel:BYTE_0
	v_or3_b32 v5, v5, v6, v7
	v_and_b32_e32 v17, 32, v3
	v_bfe_i32 v18, v0, 0, 16
	s_lshr_b32 s63, s77, 5
	v_mul_lo_u32 v5, v5, s76
	v_add_u32_e32 v2, v17, v18
	v_mul_lo_u32 v19, v4, s76
	v_add_lshl_u32 v0, v5, v2, 1
	v_add_lshl_u32 v134, v2, v19, 1
	v_cvt_f32_u32_e32 v2, s63
	s_ashr_i32 s62, s60, 31
	s_lshr_b32 s0, s62, 29
	s_add_i32 s0, s60, s0
	v_rcp_iflag_f32_e32 v2, v2
	s_ashr_i32 s14, s1, 6
	s_ashr_i32 s15, s1, 8
	s_lshl_b32 s28, s76, 8
	v_mul_f32_e32 v2, 0x4f7ffffe, v2
	v_cvt_u32_f32_e32 v2, v2
	s_ashr_i32 s3, s0, 3
	s_and_b32 s0, s0, -8
	s_lshl_b64 s[52:53], s[28:29], 1
	s_lshl_b32 s61, s14, 10
	s_lshl_b32 s20, s15, 6
	s_sub_i32 s0, s60, s0
	s_or_b32 s66, s63, 1
	s_cmp_lt_i32 s0, 0
	s_cselect_b32 s16, s66, s63
	s_sub_i32 s17, 0, s63
	v_readfirstlane_b32 s67, v2
	s_mul_i32 s0, s16, s0
	s_mul_i32 s17, s17, s67
	s_add_i32 s0, s0, s3
	s_mul_hi_u32 s17, s67, s17
	s_abs_i32 s16, s0
	s_add_i32 s67, s67, s17
	s_mul_hi_u32 s17, s16, s67
	s_mul_i32 s18, s17, s63
	s_sub_i32 s16, s16, s18
	s_ashr_i32 s3, s0, 31
	s_add_i32 s18, s17, 1
	s_sub_i32 s19, s16, s63
	s_cmp_ge_u32 s16, s63
	s_cselect_b32 s17, s18, s17
	s_cselect_b32 s16, s19, s16
	s_add_i32 s18, s17, 1
	s_cmp_ge_u32 s16, s63
	s_cselect_b32 s16, s18, s17
	s_xor_b32 s16, s16, s3
	s_sub_i32 s3, s16, s3
	s_lshl_b32 s18, s3, 3
	s_sub_i32 s16, 64, s18
	s_min_i32 s19, s16, 8
	s_sext_i32_i16 s16, s19
	v_cvt_f32_i32_e32 v3, s16
	s_mul_i32 s3, s3, s63
	s_sub_i32 s3, s0, s3
	s_sext_i32_i16 s0, s3
	v_cvt_f32_i32_e32 v2, s0
	v_rcp_iflag_f32_e32 v4, v3
	s_xor_b32 s17, s0, s16
	s_ashr_i32 s17, s17, 30
	s_or_b32 s21, s17, 1
	v_mul_f32_e32 v4, v2, v4
	v_trunc_f32_e32 v4, v4
	v_fma_f32 v2, -v4, v3, v2
	v_cvt_i32_f32_e32 v4, v4
	v_cmp_ge_f32_e64 s[16:17], |v2|, |v3|
	s_and_b64 s[16:17], s[16:17], exec
	s_cselect_b32 s0, s21, 0
	v_readfirstlane_b32 s16, v4
	s_add_i32 s0, s16, s0
	s_mul_i32 s16, s0, s19
	s_sub_i32 s3, s3, s16
	s_sext_i32_i16 s3, s3
	s_add_i32 s3, s18, s3
	s_ashr_i32 s16, s3, 31
	s_mul_i32 s16, s52, s16
	s_mul_hi_u32 s17, s52, s3
	s_bfe_u32 s18, s76, 0x10017
	s_add_i32 s16, s17, s16
	s_mul_i32 s17, s18, s3
	s_add_i32 s21, s16, s17
	s_bfe_i64 s[16:17], s[0:1], 0x100000
	s_mul_i32 s17, s52, s17
	s_mul_hi_u32 s19, s52, s16
	s_add_i32 s17, s19, s17
	s_mul_i32 s18, s18, s16
	s_add_i32 s17, s17, s18
	s_mul_i32 s16, s52, s16
	s_add_u32 s18, s46, s16
	s_addc_u32 s19, s47, s17
	s_lshl_b32 s16, s3, 8
	v_and_b32_e32 v20, 15, v21
	s_add_i32 s16, s16, s20
	v_or_b32_e32 v2, s16, v20
	v_ashrrev_i32_e32 v3, 31, v2
	s_add_i32 s68, s61, 0
	v_lshl_add_u64 v[2:3], v[2:3], 2, s[50:51]
	s_add_i32 m0, s68, 0x10000
	global_load_dword v153, v[2:3], off
	global_load_dword v152, v[2:3], off offset:64
	global_load_dword v151, v[2:3], off offset:128
	global_load_dword v150, v[2:3], off offset:192
	global_load_dword v149, v[2:3], off offset:512
	global_load_dword v148, v[2:3], off offset:576
	global_load_dword v147, v[2:3], off offset:640
	global_load_dword v144, v[2:3], off offset:704
	s_mul_i32 s22, s52, s3
	global_load_lds_dwordx4 v0, s[18:19]
	s_add_i32 m0, s68, 0x12000
	s_add_u32 s16, s18, s28
	global_load_lds_dwordx4 v130, s[18:19]
	s_addc_u32 s17, s19, 0
	s_add_i32 m0, s68, 0x14000
	v_mov_b32_e32 v131, v1
	global_load_lds_dwordx4 v0, s[16:17]
	s_add_i32 m0, s68, 0x16000
	v_lshl_add_u64 v[6:7], s[16:17], 0, v[0:1]
	v_lshl_add_u64 v[8:9], s[16:17], 0, v[130:131]
	global_load_lds_dwordx4 v130, s[16:17]
	s_add_u32 s16, s48, s22
	s_addc_u32 s17, s49, s21
	s_add_i32 s69, s68, 0x2000
	s_mov_b32 m0, s68
	s_add_u32 s22, s16, s28
	global_load_lds_dwordx4 v134, s[16:17]
	s_mov_b32 m0, s69
	s_addc_u32 s23, s17, 0
	s_add_i32 s70, s68, 0x4000
	global_load_lds_dwordx4 v132, s[16:17]
	s_mov_b32 m0, s70
	s_add_i32 s71, s68, 0x6000
	global_load_lds_dwordx4 v134, s[22:23]
	s_mov_b32 m0, s71
	v_mov_b32_e32 v135, v1
	global_load_lds_dwordx4 v132, s[22:23]
	v_mov_b32_e32 v133, v1
	s_cmp_eq_u32 s15, 1
	v_lshl_add_u64 v[2:3], s[18:19], 0, v[0:1]
	v_lshl_add_u64 v[4:5], s[18:19], 0, v[130:131]
	v_lshl_add_u64 v[10:11], s[16:17], 0, v[134:135]
	v_lshl_add_u64 v[12:13], s[16:17], 0, v[132:133]
	s_cselect_b64 s[54:55], -1, 0
	s_cmp_lg_u32 s15, 1
	s_cbranch_scc1 .LBB0_170
	s_barrier

;     __device__ void init(int M, int N, int G_, int c_, int off) { nM = M / 256; nN = N / 256; nwg = nM * nN; G = G_; c = c_ - off; if (c < 0) c += G_; }
;     __device__ bool next(int i, Unit& u) const {
;         const long L = (long)i * G + c; if (L >= nwg) return false;
; __device__ __forceinline__ void run_phase(const Params& p, LAS unsigned char* lds, int ph, bool dummy) {
;     ...
;     for (int rep = 0; rep < nstore; ++rep) {
;         EpiStore E; E.O = Ob; E.ldc = ldc; E.RS = rs_in; E.pad_ = 0; int M = MTOK, off = 0; const bf16_t* a2 = A; const bf16_t* b2 = Bt; int n2 = N;
;         if (s == 0) { a2 = MEMN + (size_t)rep * MMEM * DM; b2 = WB + rep * WO_LAYER + WO_KV; M = MMEM; n2 = 2048; E.O = KV + (size_t)rep * MMEM * 2048; E.ldc = 2048; E.RS = nullptr; off = 128 + 32 * rep; }
;         run_gemm(lds, a2, b2, M, n2, K, E, off);
.LBB0_193:
	s_mov_b32 s3, s2
	s_sub_i32 s0, s3, s0
	s_lshr_b32 s14, s1, 8
	s_ashr_i32 s1, s0, 31
	s_and_b32 s1, s1, s34
	s_add_i32 s82, s1, s0
	s_mul_i32 s28, s57, s14
	s_ashr_i32 s83, s82, 31
	v_mov_b32_e32 v14, v187
	s_cmp_lt_i32 s82, s28
	s_cselect_b64 s[0:1], -1, 0
	s_cmp_ge_i32 s82, s28
	v_readfirstlane_b32 s15, v14
	s_cbranch_scc0 .LBB0_195
	s_andn2_b64 vcc, exec, s[0:1]
	s_cbranch_vccnz .LBB0_190
	s_branch .LBB0_200
